# FoX tile: decay-row LDS reads issued with the K fragment reads; V fragments waited at their PV MFMAs
# baseline (speedup 1.0000x reference)
.LBB0_249:
	v_exp_f32_e32 v79, v138
	v_exp_f32_e32 v139, v139
	v_exp_f32_e32 v145, v136
	v_exp_f32_e32 v137, v137
	v_exp_f32_e32 v147, v68
	v_exp_f32_e32 v149, v69
	v_exp_f32_e32 v151, v70
	v_exp_f32_e32 v153, v71
	v_cvt_pk_bf16_f32 v68, v79, v139
	v_cvt_pk_bf16_f32 v69, v145, v137
	v_cvt_pk_bf16_f32 v70, v147, v149
	v_cvt_pk_bf16_f32 v71, v151, v153
	s_nop 1
	s_waitcnt lgkmcnt(14)
	v_mfma_f32_32x32x16_bf16 v[16:31], v[124:127], v[68:71], v[16:31]
	v_exp_f32_e32 v155, v72
	v_exp_f32_e32 v73, v73
	v_exp_f32_e32 v157, v74
	v_exp_f32_e32 v75, v75
	v_exp_f32_e32 v159, v76
	v_exp_f32_e32 v77, v77
	v_exp_f32_e32 v163, v60
	v_exp_f32_e32 v165, v61
	v_cvt_pk_bf16_f32 v60, v155, v73
	v_cvt_pk_bf16_f32 v61, v157, v75
	v_cvt_pk_bf16_f32 v62, v159, v77
	v_cvt_pk_bf16_f32 v63, v163, v165
	s_nop 1
	s_waitcnt lgkmcnt(12)
	v_mfma_f32_32x32x16_bf16 v[16:31], v[120:123], v[60:63], v[16:31]
	v_exp_f32_e32 v78, v64
	v_exp_f32_e32 v138, v65
	v_exp_f32_e32 v144, v48
	v_exp_f32_e32 v136, v49
	v_exp_f32_e32 v146, v50
	v_exp_f32_e32 v148, v51
	v_exp_f32_e32 v150, v66
	v_exp_f32_e32 v152, v67
	v_cvt_pk_bf16_f32 v48, v78, v138
	v_cvt_pk_bf16_f32 v49, v144, v136
	v_cvt_pk_bf16_f32 v50, v146, v148
	v_cvt_pk_bf16_f32 v51, v150, v152
	s_waitcnt lgkmcnt(10)
	v_mfma_f32_32x32x16_bf16 v[0:15], v[116:119], v[68:71], v[0:15]
	v_exp_f32_e32 v154, v54
	v_exp_f32_e32 v72, v55
	v_exp_f32_e32 v158, v56
	v_exp_f32_e32 v76, v57
	v_exp_f32_e32 v162, v58
	v_exp_f32_e32 v164, v59
	v_pk_add_f32 v[56:57], v[78:79], 0 op_sel_hi:[1,0]
	s_waitcnt lgkmcnt(8)
	v_mfma_f32_32x32x16_bf16 v[0:15], v[112:115], v[60:63], v[0:15]
	v_add_f32_e64 v58, v138, 0
	v_add_f32_e64 v59, v139, 0
	v_exp_f32_e32 v156, v52
	v_exp_f32_e32 v74, v53
	v_pk_add_f32 v[56:57], v[144:145], v[56:57]
	v_pk_add_f32 v[58:59], v[136:137], v[58:59]
	v_pk_add_f32 v[56:57], v[146:147], v[56:57]
	v_pk_add_f32 v[58:59], v[148:149], v[58:59]
	v_pk_add_f32 v[56:57], v[150:151], v[56:57]
	v_pk_add_f32 v[58:59], v[152:153], v[58:59]
	s_waitcnt lgkmcnt(6)
	v_mfma_f32_32x32x16_bf16 v[16:31], v[108:111], v[48:51], v[16:31]
	v_add_f32_e64 v56, v154, v56
	v_add_f32_e64 v57, v155, v57
	v_add_f32_e64 v58, v72, v58
	v_add_f32_e64 v59, v73, v59
	v_add_f32_e64 v56, v156, v56
	v_add_f32_e64 v57, v157, v57
	v_pk_add_f32 v[58:59], v[74:75], v[58:59]
	v_pk_add_f32 v[56:57], v[158:159], v[56:57]
	v_pk_add_f32 v[58:59], v[76:77], v[58:59]
	v_pk_add_f32 v[56:57], v[162:163], v[56:57]
	s_waitcnt lgkmcnt(2)
	v_mfma_f32_32x32x16_bf16 v[0:15], v[104:107], v[48:51], v[0:15]
	v_add_f32_e64 v48, v164, v58
	v_add_f32_e64 v49, v165, v59
	v_cvt_pk_bf16_f32 v52, v154, v72
	v_add_f32_e64 v48, v48, v56
	v_add_f32_e64 v49, v49, v57
	v_cvt_pk_bf16_f32 v53, v156, v74
	v_add_f32_e32 v48, v48, v49
	v_add_f32_e32 v143, v143, v48
	v_cvt_pk_bf16_f32 v54, v158, v76
	v_cvt_pk_bf16_f32 v55, v162, v164
	s_nop 1
	v_mfma_f32_32x32x16_bf16 v[16:31], v[96:99], v[52:55], v[16:31]
	s_waitcnt lgkmcnt(0)
	v_mfma_f32_32x32x16_bf16 v[0:15], v[100:103], v[52:55], v[0:15]

.LBB0_251:
	s_or_b32 s34, s12, s20
	s_cmp_gt_i32 s34, s18
	s_cbranch_scc1 .LBB0_250
	s_or_b32 s12, s12, s21
	s_mul_i32 s13, s12, 0x3000
	v_add_u32_e32 v52, s13, v140
	ds_read_b128 v[48:51], v52
	ds_read_b128 v[96:99], v52 offset:512
	ds_read_b128 v[100:103], v52 offset:2048
	ds_read_b128 v[104:107], v52 offset:2560
	ds_read_b128 v[108:111], v52 offset:4096
	ds_read_b128 v[112:115], v52 offset:4608
	ds_read_b128 v[116:119], v52 offset:6144
	ds_read_b128 v[120:123], v52 offset:6656
	v_lshl_add_u32 v161, s12, 10, v141
	ds_read_b128 v[144:147], v161
	ds_read_b128 v[148:151], v161 offset:128
	ds_read_b128 v[152:155], v161 offset:32
	ds_read_b128 v[156:159], v161 offset:160
	ds_read_b128 v[168:171], v161 offset:64
	ds_read_b128 v[172:175], v161 offset:192
	ds_read_b128 v[176:179], v161 offset:96
	ds_read_b128 v[180:183], v161 offset:224
	s_waitcnt lgkmcnt(15)
	v_mfma_f32_32x32x16_bf16 v[64:79], v[48:51], v[80:83], v[32:47]
	s_waitcnt lgkmcnt(14)
	v_mfma_f32_32x32x16_bf16 v[48:63], v[96:99], v[80:83], v[32:47]
	s_waitcnt lgkmcnt(13)
	v_mfma_f32_32x32x16_bf16 v[64:79], v[100:103], v[84:87], v[64:79]
	s_waitcnt lgkmcnt(12)
	v_mfma_f32_32x32x16_bf16 v[48:63], v[104:107], v[84:87], v[48:63]
	s_waitcnt lgkmcnt(11)
	v_mfma_f32_32x32x16_bf16 v[64:79], v[108:111], v[88:91], v[64:79]
	s_waitcnt lgkmcnt(10)
	v_mfma_f32_32x32x16_bf16 v[48:63], v[112:115], v[88:91], v[48:63]
	s_waitcnt lgkmcnt(9)
	v_mfma_f32_32x32x16_bf16 v[64:79], v[116:119], v[92:95], v[64:79]
	s_waitcnt lgkmcnt(8)
	v_mfma_f32_32x32x16_bf16 v[48:63], v[120:123], v[92:95], v[48:63]
	v_lshl_add_u32 v102, s12, 13, v142
	ds_read_b64_tr_b16 v[124:125], v102 offset:49152
	ds_read_b64_tr_b16 v[126:127], v102 offset:49664
	ds_read_b64_tr_b16 v[120:121], v102 offset:50176
	ds_read_b64_tr_b16 v[122:123], v102 offset:50688
	ds_read_b64_tr_b16 v[116:117], v102 offset:53248
	ds_read_b64_tr_b16 v[118:119], v102 offset:53760
	ds_read_b64_tr_b16 v[112:113], v102 offset:54272
	ds_read_b64_tr_b16 v[114:115], v102 offset:54784
	ds_read_b64_tr_b16 v[108:109], v102 offset:51200
	ds_read_b64_tr_b16 v[110:111], v102 offset:51712
	ds_read_b64_tr_b16 v[96:97], v102 offset:52224
	ds_read_b64_tr_b16 v[98:99], v102 offset:52736
	ds_read_b64_tr_b16 v[104:105], v102 offset:55296
	ds_read_b64_tr_b16 v[106:107], v102 offset:55808
	ds_read_b64_tr_b16 v[100:101], v102 offset:56320
	ds_read_b64_tr_b16 v[102:103], v102 offset:56832
	s_cmp_eq_u32 s34, s18
	s_waitcnt lgkmcnt(15)
	v_pk_add_f32 v[138:139], v[64:65], v[144:145] neg_lo:[0,1] neg_hi:[0,1]
	v_pk_add_f32 v[64:65], v[48:49], v[148:149] neg_lo:[0,1] neg_hi:[0,1]
	v_pk_add_f32 v[136:137], v[66:67], v[146:147] neg_lo:[0,1] neg_hi:[0,1]
	v_pk_add_f32 v[48:49], v[50:51], v[150:151] neg_lo:[0,1] neg_hi:[0,1]
	v_pk_add_f32 v[68:69], v[68:69], v[152:153] neg_lo:[0,1] neg_hi:[0,1]
	v_pk_add_f32 v[50:51], v[52:53], v[156:157] neg_lo:[0,1] neg_hi:[0,1]
	v_pk_add_f32 v[70:71], v[70:71], v[154:155] neg_lo:[0,1] neg_hi:[0,1]
	v_pk_add_f32 v[66:67], v[54:55], v[158:159] neg_lo:[0,1] neg_hi:[0,1]
	v_pk_add_f32 v[72:73], v[72:73], v[168:169] neg_lo:[0,1] neg_hi:[0,1]
	v_pk_add_f32 v[54:55], v[56:57], v[172:173] neg_lo:[0,1] neg_hi:[0,1]
	v_pk_add_f32 v[74:75], v[74:75], v[170:171] neg_lo:[0,1] neg_hi:[0,1]
	v_pk_add_f32 v[52:53], v[58:59], v[174:175] neg_lo:[0,1] neg_hi:[0,1]
	v_pk_add_f32 v[76:77], v[76:77], v[176:177] neg_lo:[0,1] neg_hi:[0,1]
	v_pk_add_f32 v[56:57], v[60:61], v[180:181] neg_lo:[0,1] neg_hi:[0,1]
	v_pk_add_f32 v[60:61], v[78:79], v[178:179] neg_lo:[0,1] neg_hi:[0,1]
	v_pk_add_f32 v[58:59], v[62:63], v[182:183] neg_lo:[0,1] neg_hi:[0,1]
	s_mov_b64 vcc, -1
	s_cbranch_scc1 .LBB0_254
	s_mov_b64 vcc, 0
